# code placement: K-loop and peeled copy shifted by 4 bytes so their MFMA runs start on 8-byte phase
# baseline (speedup 1.0000x reference)
.LBB0_332:
	s_add_u32 s42, s42, 0x80
	s_addc_u32 s43, s43, 0
	s_add_u32 s48, s78, 0x100
	s_addc_u32 s49, s79, 0
	s_mov_b32 s50, 0
	v_readlane_b32 s51, v232, 60
	s_cmp_eq_u32 s51, 0
	s_cbranch_scc0 .Lk_restag
	v_mov_b32_e32 v0, 0
	v_mov_b32_e32 v1, v0
	v_mov_b32_e32 v2, v0
	v_mov_b32_e32 v3, v0
	v_mov_b32_e32 v4, v0
	v_mov_b32_e32 v5, v0
	v_mov_b32_e32 v6, v0
	v_mov_b32_e32 v7, v0
	v_mov_b32_e32 v16, v0
	v_mov_b32_e32 v17, v0
	v_mov_b32_e32 v18, v0
	v_mov_b32_e32 v8, v0
	v_mov_b32_e32 v9, v0
	v_mov_b32_e32 v10, v0
	v_mov_b32_e32 v11, v0
	v_mov_b32_e32 v12, v0
	v_mov_b32_e32 v13, v0
	v_mov_b32_e32 v14, v0
	v_mov_b32_e32 v15, v0
	s_waitcnt vmcnt(6)
	s_barrier
	s_nop 0

.LBB0_586:
	s_and_b64 vcc, exec, s[0:1]
	s_cbranch_vccz .LBB0_30
	s_waitcnt lgkmcnt(0)
	s_branch .LBB0_30
	s_nop 0
